# lazy (deferred) O-rescale in the paged MLA attention compute loop: reference max kept unless a row tile-max exceeds it by 8 log2 units; f32 math unchanged
# speedup vs baseline: 1.0140x; 1.0140x over previous
.LBB0_1361:
	s_cmp_lt_u32 s64, 32
	s_cselect_b64 s[8:9], -1, 0
	s_or_b64 s[48:49], s[8:9], vcc
	s_and_saveexec_b64 s[8:9], s[48:49]
	s_cbranch_execz .LBB0_1360
	s_and_b32 s48, s64, 1
	s_mul_i32 s49, s48, 0x9400
	s_add_i32 s65, s49, 0
	v_add3_u32 v3, s65, v165, v172
	ds_read_b128 v[4:7], v3 offset:56832
	ds_read_b128 v[8:11], v173
	ds_read_b128 v[12:15], v173 offset:32
	ds_read_b128 v[176:179], v3 offset:56864
	v_and_b32_e32 v17, 64, v236
	v_xor_b32_e32 v16, 32, v236
	s_waitcnt lgkmcnt(2)
	v_mfma_f32_32x32x16_bf16 v[146:161], v[4:7], v[8:11], 0
	s_mulk_i32 s48, 0xc00
	v_add_u32_e32 v17, 64, v17
	v_add3_u32 v175, v163, s48, v170
	v_cmp_lt_i32_e64 s[48:49], v16, v17
	s_cmp_eq_u32 s64, 32
	s_cselect_b64 s[54:55], -1, 0
	v_cndmask_b32_e64 v186, v236, v16, s[48:49]
	s_waitcnt lgkmcnt(0)
	v_mfma_f32_32x32x16_bf16 v[146:161], v[176:179], v[12:15], v[146:161]
	ds_read_b128 v[4:7], v3 offset:56896
	ds_read_b128 v[8:11], v173 offset:64
	ds_read_b128 v[12:15], v173 offset:96
	ds_read_b128 v[176:179], v3 offset:56928
	s_and_b64 s[48:49], s[14:15], s[54:55]
	s_waitcnt lgkmcnt(2)
	v_mfma_f32_32x32x16_bf16 v[146:161], v[4:7], v[8:11], v[146:161]
	s_waitcnt lgkmcnt(0)
	v_mfma_f32_32x32x16_bf16 v[146:161], v[176:179], v[12:15], v[146:161]
	ds_read_b128 v[4:7], v3 offset:56960
	ds_read_b128 v[8:11], v173 offset:128
	ds_read_b128 v[12:15], v173 offset:160
	ds_read_b128 v[176:179], v3 offset:56992
	s_waitcnt lgkmcnt(2)
	v_mfma_f32_32x32x16_bf16 v[146:161], v[4:7], v[8:11], v[146:161]
	s_waitcnt lgkmcnt(0)
	v_mfma_f32_32x32x16_bf16 v[146:161], v[176:179], v[12:15], v[146:161]
	ds_read_b128 v[4:7], v3 offset:57024
	ds_read_b128 v[8:11], v173 offset:192
	ds_read_b128 v[12:15], v173 offset:224
	ds_read_b128 v[176:179], v3 offset:57056
	s_waitcnt lgkmcnt(2)
	v_mfma_f32_32x32x16_bf16 v[146:161], v[4:7], v[8:11], v[146:161]
	s_waitcnt lgkmcnt(0)
	v_mfma_f32_32x32x16_bf16 v[146:161], v[176:179], v[12:15], v[146:161]
	ds_read_b128 v[4:7], v3 offset:57088
	ds_read_b128 v[8:11], v173 offset:256
	ds_read_b128 v[12:15], v173 offset:288
	ds_read_b128 v[176:179], v3 offset:57120
	s_waitcnt lgkmcnt(2)
	v_mfma_f32_32x32x16_bf16 v[146:161], v[4:7], v[8:11], v[146:161]
	s_waitcnt lgkmcnt(0)
	v_mfma_f32_32x32x16_bf16 v[146:161], v[176:179], v[12:15], v[146:161]
	ds_read_b128 v[4:7], v3 offset:57152
	ds_read_b128 v[8:11], v173 offset:320
	ds_read_b128 v[12:15], v173 offset:352
	ds_read_b128 v[176:179], v3 offset:57184
	s_waitcnt lgkmcnt(2)
	v_mfma_f32_32x32x16_bf16 v[146:161], v[4:7], v[8:11], v[146:161]
	s_waitcnt lgkmcnt(0)
	v_mfma_f32_32x32x16_bf16 v[146:161], v[176:179], v[12:15], v[146:161]
	ds_read_b128 v[4:7], v3 offset:57216
	ds_read_b128 v[8:11], v173 offset:384
	ds_read_b128 v[12:15], v173 offset:416
	ds_read_b128 v[176:179], v3 offset:57248
	s_waitcnt lgkmcnt(2)
	v_mfma_f32_32x32x16_bf16 v[146:161], v[4:7], v[8:11], v[146:161]
	s_waitcnt lgkmcnt(0)
	v_mfma_f32_32x32x16_bf16 v[146:161], v[176:179], v[12:15], v[146:161]
	ds_read_b128 v[4:7], v3 offset:57280
	ds_read_b128 v[8:11], v173 offset:448
	ds_read_b128 v[12:15], v173 offset:480
	ds_read_b128 v[176:179], v3 offset:57312
	s_waitcnt lgkmcnt(2)
	v_mfma_f32_32x32x16_bf16 v[146:161], v[4:7], v[8:11], v[146:161]
	ds_read_b128 v[4:7], v173 offset:512
	ds_read_b128 v[8:11], v173 offset:544
	ds_read_b128 v[180:183], v3 offset:57344
	s_waitcnt lgkmcnt(3)
	v_mfma_f32_32x32x16_bf16 v[146:161], v[176:179], v[12:15], v[146:161]
	ds_read2_b32 v[16:17], v175 offset1:12
	ds_read2_b32 v[176:177], v175 offset0:24 offset1:36
	ds_read2_b32 v[178:179], v175 offset0:96 offset1:108
	ds_read2_b32 v[184:185], v175 offset0:120 offset1:132
	ds_read_b128 v[12:15], v3 offset:57376
	v_add_u32_e32 v3, 0x400, v175
	s_waitcnt lgkmcnt(5)
	v_mfma_f32_32x32x16_bf16 v[146:161], v[180:183], v[4:7], v[146:161]
	ds_read2_b32 v[4:5], v175 offset0:192 offset1:204
	ds_read2_b32 v[6:7], v175 offset0:216 offset1:228
	ds_read2_b32 v[180:181], v3 offset0:32 offset1:44
	ds_read2_b32 v[182:183], v3 offset0:56 offset1:68
	v_lshlrev_b32_e32 v175, 2, v186
	s_waitcnt lgkmcnt(4)
	v_mfma_f32_32x32x16_bf16 v[146:161], v[12:15], v[8:11], v[146:161]
	s_nop 11
	v_mul_f32_e32 v3, v146, v16
	v_mul_f32_e32 v8, v17, v147
	v_cndmask_b32_e64 v147, v3, v238, s[48:49]
	s_and_b64 s[48:49], s[16:17], s[54:55]
	v_mul_f32_e32 v9, v176, v148
	v_cndmask_b32_e64 v8, v8, v238, s[48:49]
	s_and_b64 s[48:49], s[18:19], s[54:55]
	v_mul_f32_e32 v10, v177, v149
	v_cndmask_b32_e64 v9, v9, v238, s[48:49]
	s_and_b64 s[48:49], s[20:21], s[54:55]
	v_mul_f32_e32 v11, v178, v150
	v_cndmask_b32_e64 v10, v10, v238, s[48:49]
	s_and_b64 s[48:49], s[22:23], s[54:55]
	v_mul_f32_e32 v12, v179, v151
	v_cndmask_b32_e64 v11, v11, v238, s[48:49]
	s_and_b64 s[48:49], s[24:25], s[54:55]
	v_mul_f32_e32 v13, v184, v152
	v_cndmask_b32_e64 v12, v12, v238, s[48:49]
	s_and_b64 s[48:49], s[26:27], s[54:55]
	v_mul_f32_e32 v14, v185, v153
	v_cndmask_b32_e64 v13, v13, v238, s[48:49]
	s_and_b64 s[48:49], s[28:29], s[54:55]
	s_waitcnt lgkmcnt(3)
	v_mul_f32_e32 v4, v4, v154
	v_cndmask_b32_e64 v14, v14, v238, s[48:49]
	s_and_b64 s[48:49], s[30:31], s[54:55]
	v_mul_f32_e32 v5, v5, v155
	v_cndmask_b32_e64 v4, v4, v238, s[48:49]
	s_and_b64 s[48:49], s[34:35], s[54:55]
	s_waitcnt lgkmcnt(2)
	v_mul_f32_e32 v6, v6, v156
	v_cndmask_b32_e64 v5, v5, v238, s[48:49]
	s_and_b64 s[48:49], s[36:37], s[54:55]
	v_max_f32_e32 v3, v147, v8
	v_mul_f32_e32 v7, v7, v157
	v_cndmask_b32_e64 v6, v6, v238, s[48:49]
	s_and_b64 s[48:49], s[38:39], s[54:55]
	v_max3_f32 v3, v3, v9, v10
	s_waitcnt lgkmcnt(1)
	v_mul_f32_e32 v15, v180, v158
	v_cndmask_b32_e64 v7, v7, v238, s[48:49]
	s_and_b64 s[48:49], s[40:41], s[54:55]
	v_max3_f32 v3, v3, v11, v12
	v_mul_f32_e32 v16, v181, v159
	v_cndmask_b32_e64 v15, v15, v238, s[48:49]
	s_and_b64 s[48:49], s[42:43], s[54:55]
	v_max3_f32 v3, v3, v13, v14
	s_waitcnt lgkmcnt(0)
	v_mul_f32_e32 v17, v182, v160
	v_cndmask_b32_e64 v16, v16, v238, s[48:49]
	s_and_b64 s[48:49], s[44:45], s[54:55]
	v_max3_f32 v3, v3, v4, v5
	v_mul_f32_e32 v146, v183, v161
	v_cndmask_b32_e64 v17, v17, v238, s[48:49]
	s_and_b64 s[48:49], s[46:47], s[54:55]
	v_max3_f32 v3, v3, v6, v7
	v_cndmask_b32_e64 v146, v146, v238, s[48:49]
	v_max3_f32 v3, v3, v15, v16
	v_max3_f32 v3, v3, v17, v146
	ds_bpermute_b32 v148, v175, v3
	s_waitcnt lgkmcnt(0)
	v_max_f32_e32 v148, v3, v148
	v_mov_b32_e32 v233, 0x41000000
	v_sub_f32_e32 v3, v148, v166
	v_cmp_lt_f32_e64 s[100:101], v233, v3
	s_cmp_lg_u64 s[100:101], 0
	s_cbranch_scc1 .LlazyA_rescale
	v_mov_b32_e32 v3, v166
	v_mov_b32_e32 v148, 0
.LlazyA_join:
	v_sub_f32_e32 v147, v147, v3
	v_sub_f32_e32 v8, v8, v3
	v_sub_f32_e32 v9, v9, v3
	v_sub_f32_e32 v10, v10, v3
	v_sub_f32_e32 v11, v11, v3
	v_sub_f32_e32 v12, v12, v3
	v_sub_f32_e32 v13, v13, v3
	v_sub_f32_e32 v14, v14, v3
	v_sub_f32_e32 v4, v4, v3
	v_sub_f32_e32 v5, v5, v3
	v_exp_f32_e32 v166, v147
	v_exp_f32_e32 v175, v8
	v_exp_f32_e32 v184, v9
	v_exp_f32_e32 v185, v10
	v_exp_f32_e32 v186, v11
	v_exp_f32_e32 v187, v12
	v_exp_f32_e32 v188, v13
	v_exp_f32_e32 v189, v14
	v_exp_f32_e32 v190, v4
	v_exp_f32_e32 v5, v5
	v_exp_f32_e32 v4, v148
	v_sub_f32_e32 v6, v6, v3
	v_sub_f32_e32 v7, v7, v3
	v_add_u32_e32 v10, s65, v167
	v_sub_f32_e32 v15, v15, v3
	v_sub_f32_e32 v16, v16, v3
	v_sub_f32_e32 v17, v17, v3
	v_sub_f32_e32 v146, v146, v3
	v_exp_f32_e32 v191, v6
	v_exp_f32_e32 v192, v7
	v_cvt_pk_bf16_f32 v6, v166, v175
	v_cvt_pk_bf16_f32 v7, v184, v185
	v_cvt_pk_bf16_f32 v8, v186, v187
	v_cvt_pk_bf16_f32 v9, v188, v189
	v_add3_u32 v197, v10, v169, v171
	v_exp_f32_e32 v193, v15
	v_exp_f32_e32 v194, v16
	v_exp_f32_e32 v195, v17
	v_exp_f32_e32 v196, v146
	v_add_u32_e32 v198, 0xde00, v197
	ds_read_b64_tr_b16 v[180:181], v198 offset:0
	ds_read_b64_tr_b16 v[182:183], v198 offset:4736+0
	ds_read_b64_tr_b16 v[176:177], v198 offset:64
	ds_read_b64_tr_b16 v[178:179], v198 offset:4736+64
	ds_read_b64_tr_b16 v[158:159], v198 offset:128
	ds_read_b64_tr_b16 v[160:161], v198 offset:4736+128
	ds_read_b64_tr_b16 v[154:155], v198 offset:192
	ds_read_b64_tr_b16 v[156:157], v198 offset:4736+192
	ds_read_b64_tr_b16 v[150:151], v198 offset:256
	ds_read_b64_tr_b16 v[152:153], v198 offset:4736+256
	ds_read_b64_tr_b16 v[146:147], v198 offset:320
	ds_read_b64_tr_b16 v[148:149], v198 offset:4736+320
	ds_read_b64_tr_b16 v[14:15], v198 offset:384
	ds_read_b64_tr_b16 v[16:17], v198 offset:4736+384
	ds_read_b64_tr_b16 v[10:11], v198 offset:448
	ds_read_b64_tr_b16 v[12:13], v198 offset:4736+448
	s_waitcnt lgkmcnt(0)
	v_mfma_f32_32x32x16_bf16 v[66:81], v[150:153], v[6:9], v[66:81]
	v_mfma_f32_32x32x16_bf16 v[50:65], v[146:149], v[6:9], v[50:65]
	v_mfma_f32_32x32x16_bf16 v[130:145], v[180:183], v[6:9], v[130:145]
	v_add_u32_e32 v197, 0x10300, v197
	v_mfma_f32_32x32x16_bf16 v[114:129], v[176:179], v[6:9], v[114:129]
	v_mfma_f32_32x32x16_bf16 v[98:113], v[158:161], v[6:9], v[98:113]
	v_mfma_f32_32x32x16_bf16 v[82:97], v[154:157], v[6:9], v[82:97]
	v_mfma_f32_32x32x16_bf16 v[34:49], v[14:17], v[6:9], v[34:49]
	v_mfma_f32_32x32x16_bf16 v[18:33], v[10:13], v[6:9], v[18:33]
	v_cvt_pk_bf16_f32 v6, v190, v5
	v_cvt_pk_bf16_f32 v7, v191, v192
	v_cvt_pk_bf16_f32 v8, v193, v194
	v_cvt_pk_bf16_f32 v9, v195, v196
	ds_read_b64_tr_b16 v[180:181], v197 offset:0
	ds_read_b64_tr_b16 v[182:183], v197 offset:4736+0
	ds_read_b64_tr_b16 v[176:177], v197 offset:64
	ds_read_b64_tr_b16 v[178:179], v197 offset:4736+64
	ds_read_b64_tr_b16 v[158:159], v197 offset:128
	ds_read_b64_tr_b16 v[160:161], v197 offset:4736+128
	ds_read_b64_tr_b16 v[154:155], v197 offset:192
	ds_read_b64_tr_b16 v[156:157], v197 offset:4736+192
	ds_read_b64_tr_b16 v[150:151], v197 offset:256
	ds_read_b64_tr_b16 v[152:153], v197 offset:4736+256
	ds_read_b64_tr_b16 v[146:147], v197 offset:320
	ds_read_b64_tr_b16 v[148:149], v197 offset:4736+320
	ds_read_b64_tr_b16 v[14:15], v197 offset:384
	ds_read_b64_tr_b16 v[16:17], v197 offset:4736+384
	ds_read_b64_tr_b16 v[10:11], v197 offset:448
	ds_read_b64_tr_b16 v[12:13], v197 offset:4736+448
	s_waitcnt lgkmcnt(0)
	s_nop 1
	v_mfma_f32_32x32x16_bf16 v[66:81], v[150:153], v[6:9], v[66:81]
	v_add_f32_e32 v150, 0, v166
	v_add_f32_e32 v150, v175, v150
	v_mov_b32_e32 v166, v3
	v_mfma_f32_32x32x16_bf16 v[50:65], v[146:149], v[6:9], v[50:65]
	v_add_f32_e32 v146, v184, v150
	v_add_f32_e32 v146, v185, v146
	v_add_f32_e32 v146, v186, v146
	v_add_f32_e32 v146, v187, v146
	v_add_f32_e32 v146, v188, v146
	v_add_f32_e32 v146, v189, v146
	v_add_f32_e32 v146, v190, v146
	v_add_f32_e32 v5, v5, v146
	v_mfma_f32_32x32x16_bf16 v[130:145], v[180:183], v[6:9], v[130:145]
	v_add_f32_e32 v5, v191, v5
	v_add_f32_e32 v5, v192, v5
	v_add_f32_e32 v5, v193, v5
	v_add_f32_e32 v5, v194, v5
	v_add_f32_e32 v5, v195, v5
	v_add_f32_e32 v5, v196, v5
	v_fmac_f32_e32 v5, v1, v4
	v_mfma_f32_32x32x16_bf16 v[114:129], v[176:179], v[6:9], v[114:129]
	v_mov_b32_e32 v1, v5
	v_mfma_f32_32x32x16_bf16 v[98:113], v[158:161], v[6:9], v[98:113]
	v_mfma_f32_32x32x16_bf16 v[82:97], v[154:157], v[6:9], v[82:97]
	v_mfma_f32_32x32x16_bf16 v[34:49], v[14:17], v[6:9], v[34:49]
	v_mfma_f32_32x32x16_bf16 v[18:33], v[10:13], v[6:9], v[18:33]
	s_branch .LBB0_1360
.LlazyA_rescale:
	v_max_f32_e32 v3, v166, v148
	v_sub_f32_e32 v148, v166, v3
	v_exp_f32_e32 v232, v148
	s_nop 0
	v_pk_mul_f32 v[80:81], v[80:81], v[232:233] op_sel_hi:[1,0]
	v_pk_mul_f32 v[78:79], v[78:79], v[232:233] op_sel_hi:[1,0]
	v_pk_mul_f32 v[76:77], v[76:77], v[232:233] op_sel_hi:[1,0]
	v_pk_mul_f32 v[74:75], v[74:75], v[232:233] op_sel_hi:[1,0]
	v_pk_mul_f32 v[72:73], v[72:73], v[232:233] op_sel_hi:[1,0]
	v_pk_mul_f32 v[70:71], v[70:71], v[232:233] op_sel_hi:[1,0]
	v_pk_mul_f32 v[68:69], v[68:69], v[232:233] op_sel_hi:[1,0]
	v_pk_mul_f32 v[66:67], v[66:67], v[232:233] op_sel_hi:[1,0]
	v_pk_mul_f32 v[64:65], v[64:65], v[232:233] op_sel_hi:[1,0]
	v_mul_f32_e64 v62, v62, v232
	v_mul_f32_e64 v63, v63, v232
	v_mul_f32_e64 v60, v60, v232
	v_mul_f32_e64 v61, v61, v232
	v_mul_f32_e64 v58, v58, v232
	v_mul_f32_e64 v59, v59, v232
	v_pk_mul_f32 v[56:57], v[56:57], v[232:233] op_sel_hi:[1,0]
	v_pk_mul_f32 v[54:55], v[54:55], v[232:233] op_sel_hi:[1,0]
	v_pk_mul_f32 v[52:53], v[52:53], v[232:233] op_sel_hi:[1,0]
	v_pk_mul_f32 v[50:51], v[50:51], v[232:233] op_sel_hi:[1,0]
	v_pk_mul_f32 v[144:145], v[144:145], v[232:233] op_sel_hi:[1,0]
	v_pk_mul_f32 v[142:143], v[142:143], v[232:233] op_sel_hi:[1,0]
	v_mul_f32_e64 v140, v140, v232
	v_mul_f32_e64 v141, v141, v232
	v_mul_f32_e64 v138, v138, v232
	v_mul_f32_e64 v139, v139, v232
	v_mul_f32_e64 v136, v136, v232
	v_mul_f32_e64 v137, v137, v232
	v_pk_mul_f32 v[134:135], v[134:135], v[232:233] op_sel_hi:[1,0]
	v_pk_mul_f32 v[132:133], v[132:133], v[232:233] op_sel_hi:[1,0]
	v_pk_mul_f32 v[130:131], v[130:131], v[232:233] op_sel_hi:[1,0]
	v_pk_mul_f32 v[128:129], v[128:129], v[232:233] op_sel_hi:[1,0]
	v_pk_mul_f32 v[126:127], v[126:127], v[232:233] op_sel_hi:[1,0]
	v_pk_mul_f32 v[124:125], v[124:125], v[232:233] op_sel_hi:[1,0]
	v_pk_mul_f32 v[122:123], v[122:123], v[232:233] op_sel_hi:[1,0]
	v_pk_mul_f32 v[120:121], v[120:121], v[232:233] op_sel_hi:[1,0]
	v_pk_mul_f32 v[118:119], v[118:119], v[232:233] op_sel_hi:[1,0]
	v_pk_mul_f32 v[116:117], v[116:117], v[232:233] op_sel_hi:[1,0]
	v_pk_mul_f32 v[114:115], v[114:115], v[232:233] op_sel_hi:[1,0]
	v_pk_mul_f32 v[112:113], v[112:113], v[232:233] op_sel_hi:[1,0]
	v_pk_mul_f32 v[110:111], v[110:111], v[232:233] op_sel_hi:[1,0]
	v_pk_mul_f32 v[108:109], v[108:109], v[232:233] op_sel_hi:[1,0]
	v_pk_mul_f32 v[106:107], v[106:107], v[232:233] op_sel_hi:[1,0]
	v_pk_mul_f32 v[104:105], v[104:105], v[232:233] op_sel_hi:[1,0]
	v_pk_mul_f32 v[102:103], v[102:103], v[232:233] op_sel_hi:[1,0]
	v_pk_mul_f32 v[100:101], v[100:101], v[232:233] op_sel_hi:[1,0]
	v_pk_mul_f32 v[98:99], v[98:99], v[232:233] op_sel_hi:[1,0]
	v_pk_mul_f32 v[96:97], v[96:97], v[232:233] op_sel_hi:[1,0]
	v_pk_mul_f32 v[94:95], v[94:95], v[232:233] op_sel_hi:[1,0]
	v_pk_mul_f32 v[92:93], v[92:93], v[232:233] op_sel_hi:[1,0]
	v_pk_mul_f32 v[90:91], v[90:91], v[232:233] op_sel_hi:[1,0]
	v_pk_mul_f32 v[88:89], v[88:89], v[232:233] op_sel_hi:[1,0]
	v_pk_mul_f32 v[86:87], v[86:87], v[232:233] op_sel_hi:[1,0]
	v_pk_mul_f32 v[84:85], v[84:85], v[232:233] op_sel_hi:[1,0]
	v_pk_mul_f32 v[82:83], v[82:83], v[232:233] op_sel_hi:[1,0]
	v_pk_mul_f32 v[48:49], v[48:49], v[232:233] op_sel_hi:[1,0]
	v_pk_mul_f32 v[46:47], v[46:47], v[232:233] op_sel_hi:[1,0]
	v_pk_mul_f32 v[44:45], v[44:45], v[232:233] op_sel_hi:[1,0]
	v_pk_mul_f32 v[42:43], v[42:43], v[232:233] op_sel_hi:[1,0]
	v_pk_mul_f32 v[40:41], v[40:41], v[232:233] op_sel_hi:[1,0]
	v_pk_mul_f32 v[38:39], v[38:39], v[232:233] op_sel_hi:[1,0]
	v_pk_mul_f32 v[36:37], v[36:37], v[232:233] op_sel_hi:[1,0]
	v_pk_mul_f32 v[34:35], v[34:35], v[232:233] op_sel_hi:[1,0]
	v_pk_mul_f32 v[32:33], v[32:33], v[232:233] op_sel_hi:[1,0]
	v_pk_mul_f32 v[30:31], v[30:31], v[232:233] op_sel_hi:[1,0]
	v_pk_mul_f32 v[28:29], v[28:29], v[232:233] op_sel_hi:[1,0]
	v_pk_mul_f32 v[26:27], v[26:27], v[232:233] op_sel_hi:[1,0]
	v_pk_mul_f32 v[24:25], v[24:25], v[232:233] op_sel_hi:[1,0]
	v_pk_mul_f32 v[22:23], v[22:23], v[232:233] op_sel_hi:[1,0]
	v_pk_mul_f32 v[20:21], v[20:21], v[232:233] op_sel_hi:[1,0]
	v_pk_mul_f32 v[18:19], v[18:19], v[232:233] op_sel_hi:[1,0]
	s_branch .LlazyA_join

.LBB0_1543:
	s_cmp_lt_u32 s65, 32
	s_cselect_b64 s[8:9], -1, 0
	s_or_b64 s[48:49], s[8:9], vcc
	s_and_saveexec_b64 s[8:9], s[48:49]
	s_cbranch_execz .LBB0_1542
	s_and_b32 s48, s65, 1
	s_mul_i32 s49, s48, 0x9400
	s_add_i32 s67, s49, 0
	v_add3_u32 v3, s67, v165, v172
	ds_read_b128 v[4:7], v3 offset:56832
	ds_read_b128 v[8:11], v173
	ds_read_b128 v[12:15], v173 offset:32
	ds_read_b128 v[176:179], v3 offset:56864
	v_and_b32_e32 v17, 64, v236
	v_xor_b32_e32 v16, 32, v236
	s_waitcnt lgkmcnt(2)
	v_mfma_f32_32x32x16_bf16 v[146:161], v[4:7], v[8:11], 0
	s_mulk_i32 s48, 0xc00
	v_add_u32_e32 v17, 64, v17
	v_add3_u32 v175, v163, s48, v170
	v_cmp_lt_i32_e64 s[48:49], v16, v17
	s_cmp_eq_u32 s65, 32
	s_cselect_b64 s[74:75], -1, 0
	v_cndmask_b32_e64 v186, v236, v16, s[48:49]
	s_waitcnt lgkmcnt(0)
	v_mfma_f32_32x32x16_bf16 v[146:161], v[176:179], v[12:15], v[146:161]
	ds_read_b128 v[4:7], v3 offset:56896
	ds_read_b128 v[8:11], v173 offset:64
	ds_read_b128 v[12:15], v173 offset:96
	ds_read_b128 v[176:179], v3 offset:56928
	s_and_b64 s[48:49], s[14:15], s[74:75]
	s_waitcnt lgkmcnt(2)
	v_mfma_f32_32x32x16_bf16 v[146:161], v[4:7], v[8:11], v[146:161]
	s_waitcnt lgkmcnt(0)
	v_mfma_f32_32x32x16_bf16 v[146:161], v[176:179], v[12:15], v[146:161]
	ds_read_b128 v[4:7], v3 offset:56960
	ds_read_b128 v[8:11], v173 offset:128
	ds_read_b128 v[12:15], v173 offset:160
	ds_read_b128 v[176:179], v3 offset:56992
	s_waitcnt lgkmcnt(2)
	v_mfma_f32_32x32x16_bf16 v[146:161], v[4:7], v[8:11], v[146:161]
	s_waitcnt lgkmcnt(0)
	v_mfma_f32_32x32x16_bf16 v[146:161], v[176:179], v[12:15], v[146:161]
	ds_read_b128 v[4:7], v3 offset:57024
	ds_read_b128 v[8:11], v173 offset:192
	ds_read_b128 v[12:15], v173 offset:224
	ds_read_b128 v[176:179], v3 offset:57056
	s_waitcnt lgkmcnt(2)
	v_mfma_f32_32x32x16_bf16 v[146:161], v[4:7], v[8:11], v[146:161]
	s_waitcnt lgkmcnt(0)
	v_mfma_f32_32x32x16_bf16 v[146:161], v[176:179], v[12:15], v[146:161]
	ds_read_b128 v[4:7], v3 offset:57088
	ds_read_b128 v[8:11], v173 offset:256
	ds_read_b128 v[12:15], v173 offset:288
	ds_read_b128 v[176:179], v3 offset:57120
	s_waitcnt lgkmcnt(2)
	v_mfma_f32_32x32x16_bf16 v[146:161], v[4:7], v[8:11], v[146:161]
	s_waitcnt lgkmcnt(0)
	v_mfma_f32_32x32x16_bf16 v[146:161], v[176:179], v[12:15], v[146:161]
	ds_read_b128 v[4:7], v3 offset:57152
	ds_read_b128 v[8:11], v173 offset:320
	ds_read_b128 v[12:15], v173 offset:352
	ds_read_b128 v[176:179], v3 offset:57184
	s_waitcnt lgkmcnt(2)
	v_mfma_f32_32x32x16_bf16 v[146:161], v[4:7], v[8:11], v[146:161]
	s_waitcnt lgkmcnt(0)
	v_mfma_f32_32x32x16_bf16 v[146:161], v[176:179], v[12:15], v[146:161]
	ds_read_b128 v[4:7], v3 offset:57216
	ds_read_b128 v[8:11], v173 offset:384
	ds_read_b128 v[12:15], v173 offset:416
	ds_read_b128 v[176:179], v3 offset:57248
	s_waitcnt lgkmcnt(2)
	v_mfma_f32_32x32x16_bf16 v[146:161], v[4:7], v[8:11], v[146:161]
	s_waitcnt lgkmcnt(0)
	v_mfma_f32_32x32x16_bf16 v[146:161], v[176:179], v[12:15], v[146:161]
	ds_read_b128 v[4:7], v3 offset:57280
	ds_read_b128 v[8:11], v173 offset:448
	ds_read_b128 v[12:15], v173 offset:480
	ds_read_b128 v[176:179], v3 offset:57312
	s_waitcnt lgkmcnt(2)
	v_mfma_f32_32x32x16_bf16 v[146:161], v[4:7], v[8:11], v[146:161]
	ds_read_b128 v[4:7], v173 offset:512
	ds_read_b128 v[8:11], v173 offset:544
	ds_read_b128 v[180:183], v3 offset:57344
	s_waitcnt lgkmcnt(3)
	v_mfma_f32_32x32x16_bf16 v[146:161], v[176:179], v[12:15], v[146:161]
	ds_read2_b32 v[16:17], v175 offset1:12
	ds_read2_b32 v[176:177], v175 offset0:24 offset1:36
	ds_read2_b32 v[178:179], v175 offset0:96 offset1:108
	ds_read2_b32 v[184:185], v175 offset0:120 offset1:132
	ds_read_b128 v[12:15], v3 offset:57376
	v_add_u32_e32 v3, 0x400, v175
	s_waitcnt lgkmcnt(5)
	v_mfma_f32_32x32x16_bf16 v[146:161], v[180:183], v[4:7], v[146:161]
	ds_read2_b32 v[4:5], v175 offset0:192 offset1:204
	ds_read2_b32 v[6:7], v175 offset0:216 offset1:228
	ds_read2_b32 v[180:181], v3 offset0:32 offset1:44
	ds_read2_b32 v[182:183], v3 offset0:56 offset1:68
	v_lshlrev_b32_e32 v175, 2, v186
	s_waitcnt lgkmcnt(4)
	v_mfma_f32_32x32x16_bf16 v[146:161], v[12:15], v[8:11], v[146:161]
	s_nop 11
	v_mul_f32_e32 v3, v146, v16
	v_mul_f32_e32 v8, v17, v147
	v_cndmask_b32_e64 v147, v3, v238, s[48:49]
	s_and_b64 s[48:49], s[16:17], s[74:75]
	v_mul_f32_e32 v9, v176, v148
	v_cndmask_b32_e64 v8, v8, v238, s[48:49]
	s_and_b64 s[48:49], s[18:19], s[74:75]
	v_mul_f32_e32 v10, v177, v149
	v_cndmask_b32_e64 v9, v9, v238, s[48:49]
	s_and_b64 s[48:49], s[20:21], s[74:75]
	v_mul_f32_e32 v11, v178, v150
	v_cndmask_b32_e64 v10, v10, v238, s[48:49]
	s_and_b64 s[48:49], s[22:23], s[74:75]
	v_mul_f32_e32 v12, v179, v151
	v_cndmask_b32_e64 v11, v11, v238, s[48:49]
	s_and_b64 s[48:49], s[24:25], s[74:75]
	v_mul_f32_e32 v13, v184, v152
	v_cndmask_b32_e64 v12, v12, v238, s[48:49]
	s_and_b64 s[48:49], s[26:27], s[74:75]
	v_mul_f32_e32 v14, v185, v153
	v_cndmask_b32_e64 v13, v13, v238, s[48:49]
	s_and_b64 s[48:49], s[28:29], s[74:75]
	s_waitcnt lgkmcnt(3)
	v_mul_f32_e32 v4, v4, v154
	v_cndmask_b32_e64 v14, v14, v238, s[48:49]
	s_and_b64 s[48:49], s[30:31], s[74:75]
	v_mul_f32_e32 v5, v5, v155
	v_cndmask_b32_e64 v4, v4, v238, s[48:49]
	s_and_b64 s[48:49], s[34:35], s[74:75]
	s_waitcnt lgkmcnt(2)
	v_mul_f32_e32 v6, v6, v156
	v_cndmask_b32_e64 v5, v5, v238, s[48:49]
	s_and_b64 s[48:49], s[36:37], s[74:75]
	v_max_f32_e32 v3, v147, v8
	v_mul_f32_e32 v7, v7, v157
	v_cndmask_b32_e64 v6, v6, v238, s[48:49]
	s_and_b64 s[48:49], s[38:39], s[74:75]
	v_max3_f32 v3, v3, v9, v10
	s_waitcnt lgkmcnt(1)
	v_mul_f32_e32 v15, v180, v158
	v_cndmask_b32_e64 v7, v7, v238, s[48:49]
	s_and_b64 s[48:49], s[40:41], s[74:75]
	v_max3_f32 v3, v3, v11, v12
	v_mul_f32_e32 v16, v181, v159
	v_cndmask_b32_e64 v15, v15, v238, s[48:49]
	s_and_b64 s[48:49], s[42:43], s[74:75]
	v_max3_f32 v3, v3, v13, v14
	s_waitcnt lgkmcnt(0)
	v_mul_f32_e32 v17, v182, v160
	v_cndmask_b32_e64 v16, v16, v238, s[48:49]
	s_and_b64 s[48:49], s[44:45], s[74:75]
	v_max3_f32 v3, v3, v4, v5
	v_mul_f32_e32 v146, v183, v161
	v_cndmask_b32_e64 v17, v17, v238, s[48:49]
	s_and_b64 s[48:49], s[46:47], s[74:75]
	v_max3_f32 v3, v3, v6, v7
	v_cndmask_b32_e64 v146, v146, v238, s[48:49]
	v_max3_f32 v3, v3, v15, v16
	v_max3_f32 v3, v3, v17, v146
	ds_bpermute_b32 v148, v175, v3
	s_waitcnt lgkmcnt(0)
	v_max_f32_e32 v148, v3, v148
	v_mov_b32_e32 v233, 0x41000000
	v_sub_f32_e32 v3, v148, v166
	v_cmp_lt_f32_e64 s[100:101], v233, v3
	s_cmp_lg_u64 s[100:101], 0
	s_cbranch_scc1 .LlazyB_rescale
	v_mov_b32_e32 v3, v166
	v_mov_b32_e32 v148, 0
.LlazyB_join:
	v_sub_f32_e32 v147, v147, v3
	v_sub_f32_e32 v8, v8, v3
	v_sub_f32_e32 v9, v9, v3
	v_sub_f32_e32 v10, v10, v3
	v_sub_f32_e32 v11, v11, v3
	v_sub_f32_e32 v12, v12, v3
	v_sub_f32_e32 v13, v13, v3
	v_sub_f32_e32 v14, v14, v3
	v_sub_f32_e32 v4, v4, v3
	v_sub_f32_e32 v5, v5, v3
	v_exp_f32_e32 v166, v147
	v_exp_f32_e32 v175, v8
	v_exp_f32_e32 v184, v9
	v_exp_f32_e32 v185, v10
	v_exp_f32_e32 v186, v11
	v_exp_f32_e32 v187, v12
	v_exp_f32_e32 v188, v13
	v_exp_f32_e32 v189, v14
	v_exp_f32_e32 v190, v4
	v_exp_f32_e32 v5, v5
	v_exp_f32_e32 v4, v148
	v_sub_f32_e32 v6, v6, v3
	v_sub_f32_e32 v7, v7, v3
	v_add_u32_e32 v10, s67, v167
	v_sub_f32_e32 v15, v15, v3
	v_sub_f32_e32 v16, v16, v3
	v_sub_f32_e32 v17, v17, v3
	v_sub_f32_e32 v146, v146, v3
	v_exp_f32_e32 v191, v6
	v_exp_f32_e32 v192, v7
	v_cvt_pk_bf16_f32 v6, v166, v175
	v_cvt_pk_bf16_f32 v7, v184, v185
	v_cvt_pk_bf16_f32 v8, v186, v187
	v_cvt_pk_bf16_f32 v9, v188, v189
	v_add3_u32 v197, v10, v169, v171
	v_exp_f32_e32 v193, v15
	v_exp_f32_e32 v194, v16
	v_exp_f32_e32 v195, v17
	v_exp_f32_e32 v196, v146
	v_add_u32_e32 v198, 0xde00, v197
	ds_read_b64_tr_b16 v[180:181], v198 offset:0
	ds_read_b64_tr_b16 v[182:183], v198 offset:4736+0
	ds_read_b64_tr_b16 v[176:177], v198 offset:64
	ds_read_b64_tr_b16 v[178:179], v198 offset:4736+64
	ds_read_b64_tr_b16 v[158:159], v198 offset:128
	ds_read_b64_tr_b16 v[160:161], v198 offset:4736+128
	ds_read_b64_tr_b16 v[154:155], v198 offset:192
	ds_read_b64_tr_b16 v[156:157], v198 offset:4736+192
	ds_read_b64_tr_b16 v[150:151], v198 offset:256
	ds_read_b64_tr_b16 v[152:153], v198 offset:4736+256
	ds_read_b64_tr_b16 v[146:147], v198 offset:320
	ds_read_b64_tr_b16 v[148:149], v198 offset:4736+320
	ds_read_b64_tr_b16 v[14:15], v198 offset:384
	ds_read_b64_tr_b16 v[16:17], v198 offset:4736+384
	ds_read_b64_tr_b16 v[10:11], v198 offset:448
	ds_read_b64_tr_b16 v[12:13], v198 offset:4736+448
	s_waitcnt lgkmcnt(0)
	v_mfma_f32_32x32x16_bf16 v[66:81], v[150:153], v[6:9], v[66:81]
	v_mfma_f32_32x32x16_bf16 v[50:65], v[146:149], v[6:9], v[50:65]
	v_mfma_f32_32x32x16_bf16 v[130:145], v[180:183], v[6:9], v[130:145]
	v_add_u32_e32 v197, 0x10300, v197
	v_mfma_f32_32x32x16_bf16 v[114:129], v[176:179], v[6:9], v[114:129]
	v_mfma_f32_32x32x16_bf16 v[98:113], v[158:161], v[6:9], v[98:113]
	v_mfma_f32_32x32x16_bf16 v[82:97], v[154:157], v[6:9], v[82:97]
	v_mfma_f32_32x32x16_bf16 v[34:49], v[14:17], v[6:9], v[34:49]
	v_mfma_f32_32x32x16_bf16 v[18:33], v[10:13], v[6:9], v[18:33]
	v_cvt_pk_bf16_f32 v6, v190, v5
	v_cvt_pk_bf16_f32 v7, v191, v192
	v_cvt_pk_bf16_f32 v8, v193, v194
	v_cvt_pk_bf16_f32 v9, v195, v196
	ds_read_b64_tr_b16 v[180:181], v197 offset:0
	ds_read_b64_tr_b16 v[182:183], v197 offset:4736+0
	ds_read_b64_tr_b16 v[176:177], v197 offset:64
	ds_read_b64_tr_b16 v[178:179], v197 offset:4736+64
	ds_read_b64_tr_b16 v[158:159], v197 offset:128
	ds_read_b64_tr_b16 v[160:161], v197 offset:4736+128
	ds_read_b64_tr_b16 v[154:155], v197 offset:192
	ds_read_b64_tr_b16 v[156:157], v197 offset:4736+192
	ds_read_b64_tr_b16 v[150:151], v197 offset:256
	ds_read_b64_tr_b16 v[152:153], v197 offset:4736+256
	ds_read_b64_tr_b16 v[146:147], v197 offset:320
	ds_read_b64_tr_b16 v[148:149], v197 offset:4736+320
	ds_read_b64_tr_b16 v[14:15], v197 offset:384
	ds_read_b64_tr_b16 v[16:17], v197 offset:4736+384
	ds_read_b64_tr_b16 v[10:11], v197 offset:448
	ds_read_b64_tr_b16 v[12:13], v197 offset:4736+448
	s_waitcnt lgkmcnt(0)
	s_nop 1
	v_mfma_f32_32x32x16_bf16 v[66:81], v[150:153], v[6:9], v[66:81]
	v_add_f32_e32 v150, 0, v166
	v_add_f32_e32 v150, v175, v150
	v_mov_b32_e32 v166, v3
	v_mfma_f32_32x32x16_bf16 v[50:65], v[146:149], v[6:9], v[50:65]
	v_add_f32_e32 v146, v184, v150
	v_add_f32_e32 v146, v185, v146
	v_add_f32_e32 v146, v186, v146
	v_add_f32_e32 v146, v187, v146
	v_add_f32_e32 v146, v188, v146
	v_add_f32_e32 v146, v189, v146
	v_add_f32_e32 v146, v190, v146
	v_add_f32_e32 v5, v5, v146
	v_mfma_f32_32x32x16_bf16 v[130:145], v[180:183], v[6:9], v[130:145]
	v_add_f32_e32 v5, v191, v5
	v_add_f32_e32 v5, v192, v5
	v_add_f32_e32 v5, v193, v5
	v_add_f32_e32 v5, v194, v5
	v_add_f32_e32 v5, v195, v5
	v_add_f32_e32 v5, v196, v5
	v_fmac_f32_e32 v5, v1, v4
	v_mfma_f32_32x32x16_bf16 v[114:129], v[176:179], v[6:9], v[114:129]
	v_mov_b32_e32 v1, v5
	v_mfma_f32_32x32x16_bf16 v[98:113], v[158:161], v[6:9], v[98:113]
	v_mfma_f32_32x32x16_bf16 v[82:97], v[154:157], v[6:9], v[82:97]
	v_mfma_f32_32x32x16_bf16 v[34:49], v[14:17], v[6:9], v[34:49]
	v_mfma_f32_32x32x16_bf16 v[18:33], v[10:13], v[6:9], v[18:33]
	s_branch .LBB0_1542

	.amdhsa_kernel _ZN2fk6k_megaENS_1PE
		.amdhsa_group_segment_fixed_size 0
		.amdhsa_private_segment_fixed_size 0
		.amdhsa_kernarg_size 520
		.amdhsa_user_sgpr_count 2
		.amdhsa_user_sgpr_dispatch_ptr 0
		.amdhsa_user_sgpr_queue_ptr 0
		.amdhsa_user_sgpr_kernarg_segment_ptr 1
		.amdhsa_user_sgpr_dispatch_id 0
		.amdhsa_user_sgpr_kernarg_preload_length 0
		.amdhsa_user_sgpr_kernarg_preload_offset 0
		.amdhsa_user_sgpr_private_segment_size 0
		.amdhsa_uses_dynamic_stack 0
		.amdhsa_enable_private_segment 0
		.amdhsa_system_sgpr_workgroup_id_x 1
		.amdhsa_system_sgpr_workgroup_id_y 0
		.amdhsa_system_sgpr_workgroup_id_z 0
		.amdhsa_system_sgpr_workgroup_info 0
		.amdhsa_system_vgpr_workitem_id 0
		.amdhsa_next_free_vgpr 256
		.amdhsa_next_free_sgpr 102
		.amdhsa_accum_offset 256
		.amdhsa_reserve_vcc 1
		.amdhsa_float_round_mode_32 0
		.amdhsa_float_round_mode_16_64 0
		.amdhsa_float_denorm_mode_32 3
		.amdhsa_float_denorm_mode_16_64 3
		.amdhsa_dx10_clamp 1
		.amdhsa_ieee_mode 1
		.amdhsa_fp16_overflow 0
		.amdhsa_tg_split 0
		.amdhsa_exception_fp_ieee_invalid_op 0
		.amdhsa_exception_fp_denorm_src 0
		.amdhsa_exception_fp_ieee_div_zero 0
		.amdhsa_exception_fp_ieee_overflow 0
		.amdhsa_exception_fp_ieee_underflow 0
		.amdhsa_exception_fp_ieee_inexact 0
		.amdhsa_exception_int_div_zero 0
	.end_amdhsa_kernel

amdhsa.kernels:
  - .agpr_count:     0
    .args:
      - .offset:         0
        .size:           264
        .value_kind:     by_value
      - .offset:         264
        .size:           4
        .value_kind:     hidden_block_count_x
      - .offset:         268
        .size:           4
        .value_kind:     hidden_block_count_y
      - .offset:         272
        .size:           4
        .value_kind:     hidden_block_count_z
      - .offset:         276
        .size:           2
        .value_kind:     hidden_group_size_x
      - .offset:         278
        .size:           2
        .value_kind:     hidden_group_size_y
      - .offset:         280
        .size:           2
        .value_kind:     hidden_group_size_z
      - .offset:         282
        .size:           2
        .value_kind:     hidden_remainder_x
      - .offset:         284
        .size:           2
        .value_kind:     hidden_remainder_y
      - .offset:         286
        .size:           2
        .value_kind:     hidden_remainder_z
      - .offset:         304
        .size:           8
        .value_kind:     hidden_global_offset_x
      - .offset:         312
        .size:           8
        .value_kind:     hidden_global_offset_y
      - .offset:         320
        .size:           8
        .value_kind:     hidden_global_offset_z
      - .offset:         328
        .size:           2
        .value_kind:     hidden_grid_dims
      - .offset:         384
        .size:           4
        .value_kind:     hidden_dynamic_lds_size
    .group_segment_fixed_size: 0
    .kernarg_segment_align: 8
    .kernarg_segment_size: 520
    .language:       OpenCL C
    .language_version:
      - 2
      - 0
    .max_flat_workgroup_size: 512
    .name:           _ZN2fk6k_megaENS_1PE
    .private_segment_fixed_size: 0
    .sgpr_count:     108
    .sgpr_spill_count: 208
    .symbol:         _ZN2fk6k_megaENS_1PE.kd
    .uniform_work_group_size: 1
    .uses_dynamic_stack: false
    .vgpr_count:     256
    .vgpr_spill_count: 0
    .wavefront_size: 64
